# hand-written pipelined attention tile loop, new K/V row permutation (4 runs of 4 rows per 16 positions), nt output stores; pass1 prefetch
# baseline (speedup 1.0000x reference)
.LBB0_92:
	s_mov_b64 s[24:25], 0x80
	s_and_b32 s1, s1, 3
	s_add_i32 m0, s19, 0x18000
	v_lshl_add_u64 v[6:7], v[6:7], 0, s[24:25]
	s_lshl_b32 s3, s2, 13
	s_lshl_b32 s50, s1, 5
	s_lshl_b32 s1, s1, 12
	s_waitcnt vmcnt(2)
	s_barrier
	global_load_lds_dwordx4 v[6:7], off
	v_lshl_add_u64 v[4:5], v[4:5], 0, s[24:25]
	s_add_i32 m0, s19, 0x1a000
	s_add_i32 s51, s19, 0x8000
	s_add_i32 s52, s19, 0xa000
	global_load_lds_dwordx4 v[4:5], off
	v_lshl_add_u64 v[0:1], v[0:1], 0, s[24:25]
	s_mov_b32 m0, s51
	s_add_u32 s4, s10, 0x40080
	global_load_lds_dwordx4 v[0:1], off
	v_lshl_add_u64 v[0:1], v[2:3], 0, s[24:25]
	s_mov_b32 m0, s52
	s_addc_u32 s5, s11, 0
	global_load_lds_dwordx4 v[0:1], off
	s_add_i32 m0, s19, 0x1c000
	v_lshl_add_u64 v[0:1], s[4:5], 0, v[154:155]
	global_load_lds_dwordx4 v[0:1], off
	v_lshl_add_u64 v[0:1], s[4:5], 0, v[158:159]
	s_add_i32 m0, s19, 0x1e000
	s_cmpk_lt_u32 s0, 0x100
	global_load_lds_dwordx4 v[0:1], off
	v_bfe_u32 v1, v8, 4, 2
	v_and_b32_e32 v0, 15, v8
	v_lshlrev_b32_e32 v2, 4, v1
	v_lshl_or_b32 v147, s2, 6, v0
	v_lshl_or_b32 v0, v0, 6, v2
	v_lshlrev_b32_e32 v2, 2, v8
	v_and_b32_e32 v2, 32, v2
	v_bitop3_b32 v3, v0, s3, v2 bitop3:0xde
	v_bitop3_b32 v149, v0, s1, v2 bitop3:0xde
	v_lshlrev_b32_e32 v0, 14, v9
	v_and_b32_e32 v0, 0xffff8000, v0
	v_lshlrev_b32_e32 v162, 3, v1
	v_cmp_eq_u32_e32 vcc, 0, v1
	v_cmp_gt_u32_e64 s[14:15], 2, v1
	v_lshl_add_u32 v0, v10, 11, v0
	v_and_b32_e32 v1, 1, v9
	v_lshl_or_b32 v0, v1, 6, v0
	v_lshl_add_u32 v166, v11, 1, v0
	v_lshlrev_b32_e32 v0, 14, v12
	v_and_b32_e32 v0, 0xffff8000, v0
	s_waitcnt vmcnt(6)
	s_cselect_b64 s[26:27], -1, 0
	s_bitcmp0_b32 s0, 6
	v_lshl_add_u32 v0, v13, 11, v0
	v_and_b32_e32 v1, 1, v12
	s_cselect_b64 s[28:29], -1, 0
	v_cndmask_b32_e64 v164, 1.0, -1.0, vcc
	v_lshl_or_b32 v0, v1, 6, v0
	s_add_i32 s57, 0, 0x10000
	s_add_i32 s58, 0, 0x14000
	s_movk_i32 s30, 0xf400
	s_movk_i32 s34, 0xf500
	s_mov_b32 s53, 0x8000
	s_ashr_i32 s54, s84, 31
	s_mov_b32 s55, s84
	s_ashr_i32 s56, s88, 31
	v_mov_b32_e32 v165, v164
	v_mov_b32_e32 v167, v161
	v_lshl_add_u32 v168, v14, 1, v0
	v_mov_b32_e32 v169, v161
	v_add_u32_e32 v151, s57, v149
	v_add_u32_e32 v182, s58, v149
	v_add_u32_e32 v183, 0, v3
	s_movk_i32 s59, 0x1400
	s_mov_b32 s31, -1
	s_mov_b32 s35, -1
	s_movk_i32 s60, 0x7f80
	s_movk_i32 s61, 0x7f70
	s_movk_i32 s62, 0x7f60
	s_movk_i32 s63, 0x7f50
	v_mov_b32_e32 v184, 0xfcf
	v_mov_b32_e32 v185, 0x3fcf
	v_mov_b32_e32 v186, 0x7ffff000
	v_mov_b32_e32 v187, 0xffffc000
	v_mov_b32_e32 v188, 0xc00
	v_mov_b32_e32 v189, 0x3000
	v_mov_b32_e32 v190, 0x3ff
	v_mov_b32_e32 v191, 0xfff
	v_mbcnt_hi_u32_b32 v192, -1, v163
	v_mov_b32_e32 v193, 0x3e000000
	v_mov_b32_e32 v194, 0xfdf
	v_mov_b32_e32 v195, 0x3fdf
	v_mov_b32_e32 v196, 0x3ff
	v_mov_b32_e32 v197, 0xfff
	v_mov_b32_e32 v198, 0xfef
	v_mov_b32_e32 v199, 0x3fef
	v_mov_b32_e32 v200, 0x3ff
	v_mov_b32_e32 v201, 0xfff
	v_mov_b32_e32 v202, 0xfff
	v_mov_b32_e32 v203, 0x3fff
	v_mov_b32_e32 v204, 0x3ff
	v_mov_b32_e32 v205, 0xfff
	s_mov_b32 s64, 0
	s_barrier
	s_branch .LBB0_95

.LBB0_108:
	s_cmp_lt_i32 s18, 6
	s_cselect_b64 s[12:13], -1, 0
	s_cmp_gt_i32 s18, 5
	s_cselect_b64 s[10:11], -1, 0
	v_mov_b64_e32 v[174:175], 0
	s_and_b64 vcc, exec, s[10:11]
	s_cbranch_vccnz .LBB0_110
	v_cmp_gt_i32_e32 vcc, s53, v206
	v_lshrrev_b32_e32 v160, 2, v206
	s_nop 0
	v_cndmask_b32_e64 v171, 10, 12, vcc
	v_cndmask_b32_e32 v170, v186, v187, vcc
	v_cndmask_b32_e32 v172, v188, v189, vcc
	v_cndmask_b32_e32 v173, v190, v191, vcc
	v_lshlrev_b32_e32 v171, v171, v206
	v_and_b32_e32 v170, v170, v206
	v_and_b32_e32 v171, v171, v172
	v_and_b32_e32 v160, v173, v160
	v_or3_b32 v174, v160, v170, v171
	v_ashrrev_i32_e32 v175, 31, v174

.LBB0_129:
	v_cndmask_b32_e64 v128, 0, 1, s[12:13]
	v_cmp_ne_u32_e64 s[10:11], 1, v128
	s_andn2_b64 vcc, exec, s[12:13]
	v_mov_b64_e32 v[128:129], 0
	s_cbranch_vccnz .LBB0_131
	v_cmp_gt_i32_e32 vcc, s53, v134
	v_lshrrev_b32_e32 v128, 2, v134
	s_nop 0
	v_cndmask_b32_e64 v130, 10, 12, vcc
	v_cndmask_b32_e32 v129, v186, v187, vcc
	v_cndmask_b32_e32 v131, v188, v189, vcc
	v_cndmask_b32_e32 v132, v196, v197, vcc
	v_lshlrev_b32_e32 v130, v130, v134
	v_and_b32_e32 v129, v129, v206
	v_and_b32_e32 v130, v130, v131
	v_and_b32_e32 v128, v132, v128
	v_or3_b32 v128, v128, v129, v130
	v_ashrrev_i32_e32 v129, 31, v128

.LBB0_150:
	v_cmp_gt_i32_e32 vcc, s53, v118
	v_lshrrev_b32_e32 v112, 2, v118
	s_nop 0
	v_cndmask_b32_e64 v114, 10, 12, vcc
	v_cndmask_b32_e32 v113, v186, v187, vcc
	v_cndmask_b32_e32 v115, v188, v189, vcc
	v_cndmask_b32_e32 v116, v200, v201, vcc
	v_lshlrev_b32_e32 v114, v114, v118
	v_and_b32_e32 v113, v113, v206
	v_and_b32_e32 v114, v114, v115
	v_and_b32_e32 v112, v116, v112
	v_or3_b32 v112, v112, v113, v114
	v_ashrrev_i32_e32 v113, 31, v112

.LBB0_170:
	v_cmp_gt_i32_e32 vcc, s53, v102
	v_lshrrev_b32_e32 v96, 2, v102
	s_nop 0
	v_cndmask_b32_e64 v98, 10, 12, vcc
	v_cndmask_b32_e32 v97, v186, v187, vcc
	v_cndmask_b32_e32 v99, v188, v189, vcc
	v_cndmask_b32_e32 v100, v204, v205, vcc
	v_lshlrev_b32_e32 v98, v98, v102
	v_and_b32_e32 v97, v97, v206
	v_and_b32_e32 v98, v98, v99
	v_and_b32_e32 v96, v100, v96
	v_or3_b32 v96, v96, v97, v98
	v_ashrrev_i32_e32 v97, 31, v96

.LBB0_190:
	v_cmp_gt_i32_e32 vcc, s60, v206
	v_lshrrev_b32_e32 v80, 2, v86
	s_nop 0
	v_cndmask_b32_e64 v82, 10, 12, vcc
	v_cndmask_b32_e32 v81, v186, v187, vcc
	v_cndmask_b32_e32 v83, v188, v189, vcc
	v_cndmask_b32_e32 v84, v190, v191, vcc
	v_lshlrev_b32_e32 v82, v82, v86
	v_and_b32_e32 v81, v81, v86
	v_and_b32_e32 v82, v82, v83
	v_and_b32_e32 v80, v84, v80
	v_or3_b32 v80, v80, v81, v82
	v_ashrrev_i32_e32 v81, 31, v80

.LBB0_210:
	v_cmp_gt_i32_e32 vcc, s61, v206
	v_lshrrev_b32_e32 v64, 2, v70
	s_nop 0
	v_cndmask_b32_e64 v66, 10, 12, vcc
	v_cndmask_b32_e32 v65, v186, v187, vcc
	v_cndmask_b32_e32 v67, v188, v189, vcc
	v_cndmask_b32_e32 v68, v196, v197, vcc
	v_lshlrev_b32_e32 v66, v66, v70
	v_and_b32_e32 v65, v65, v86
	v_and_b32_e32 v66, v66, v67
	v_and_b32_e32 v64, v68, v64
	v_or3_b32 v64, v64, v65, v66
	v_ashrrev_i32_e32 v65, 31, v64

.LBB0_230:
	v_cmp_gt_i32_e32 vcc, s62, v206
	v_lshrrev_b32_e32 v48, 2, v54
	s_nop 0
	v_cndmask_b32_e64 v50, 10, 12, vcc
	v_cndmask_b32_e32 v49, v186, v187, vcc
	v_cndmask_b32_e32 v51, v188, v189, vcc
	v_cndmask_b32_e32 v52, v200, v201, vcc
	v_lshlrev_b32_e32 v50, v50, v54
	v_and_b32_e32 v49, v49, v86
	v_and_b32_e32 v50, v50, v51
	v_and_b32_e32 v48, v52, v48
	v_or3_b32 v48, v48, v49, v50
	v_ashrrev_i32_e32 v49, 31, v48

.LBB0_250:
	v_cmp_gt_i32_e32 vcc, s63, v206
	v_lshrrev_b32_e32 v32, 2, v38
	s_nop 0
	v_cndmask_b32_e64 v34, 10, 12, vcc
	v_cndmask_b32_e32 v33, v186, v187, vcc
	v_cndmask_b32_e32 v35, v188, v189, vcc
	v_cndmask_b32_e32 v36, v204, v205, vcc
	v_lshlrev_b32_e32 v34, v34, v38
	v_and_b32_e32 v33, v33, v86
	v_and_b32_e32 v34, v34, v35
	v_and_b32_e32 v32, v36, v32
	v_or3_b32 v32, v32, v33, v34
	v_ashrrev_i32_e32 v33, 31, v32

.Latt_entry:
	s_mov_b64 exec, -1
	v_readlane_b32 s4, v254, 0
	v_readlane_b32 s5, v254, 1
	v_readlane_b32 s6, v254, 42
	v_readlane_b32 s7, v254, 43
	v_readlane_b32 s8, v254, 46
	v_readlane_b32 s10, v254, 53
	v_readfirstlane_b32 s0, v145
	s_movk_i32 s78, 0x90
	s_movk_i32 s79, 0x110
	s_mov_b32 s80, 0x12100
	s_movk_i32 s82, 0x4000
	s_movk_i32 s83, 0x1000
	s_mov_b32 s84, 0xc000
	s_mov_b32 s85, 0x7ffff000
	s_lshr_b32 s0, s0, 6
	s_mul_i32 s1, s0, 0x1200
	s_add_i32 s1, s1, 0x12500
	s_mov_b32 s39, 0
	s_mov_b32 s11, 0
	v_and_b32_e32 v241, 63, v145
	v_and_b32_e32 v160, 15, v145
	v_bfe_u32 v179, v145, 4, 2
	v_lshlrev_b32_e32 v161, 4, v179
	v_lshlrev_b32_e32 v169, 2, v179
	v_and_b32_e32 v182, 7, v145
	v_lshlrev_b32_e32 v162, 4, v182
	v_bfe_u32 v164, v145, 3, 3
	v_mad_u32_u24 v165, v164, s78, v162
	v_add_u32_e32 v165, s1, v165
	v_bfe_u32 v179, v145, 2, 2
	v_add_u32_e32 v179, v179, v169
	v_and_b32_e32 v182, 3, v145
	v_lshlrev_b32_e32 v182, 3, v182
	v_mad_u32_u24 v166, v179, s78, v182
	v_add_u32_e32 v166, s1, v166
	v_xor_b32_e32 v179, 16, v241
	v_lshlrev_b32_e32 v167, 2, v179
	v_xor_b32_e32 v179, 32, v241
	v_lshlrev_b32_e32 v168, 2, v179
	v_sub_u32_e32 v179, v169, v160
	v_cmp_ge_i32_e64 s[54:55], v179, 0
	v_cmp_le_i32_e64 s[62:63], v179, 0
	v_cmp_ge_i32_e64 s[56:57], v179, -1
	v_cmp_le_i32_e64 s[64:65], v179, -1
	v_cmp_ge_i32_e64 s[58:59], v179, -2
	v_cmp_le_i32_e64 s[66:67], v179, -2
	v_cmp_ge_i32_e64 s[60:61], v179, -3
	v_cmp_le_i32_e64 s[68:69], v179, -3
	v_lshrrev_b32_e32 v179, 1, v145
	v_lshrrev_b32_e32 v182, 4, v179
	v_add_u32_e32 v182, v182, v179
	v_and_b32_e32 v183, 1, v145
	v_lshlrev_b32_e32 v147, 7, v183
	v_mad_u32_u24 v170, v182, s79, v147
	v_lshl_add_u32 v171, v179, 2, s80
	v_lshlrev_b32_e32 v182, 11, v179
	v_lshl_add_u32 v172, v183, 6, v182
	v_mov_b32_e32 v202, 0
	v_mov_b32_e32 v203, 0
	s_lshr_b32 s2, s10, 3
	s_and_b32 s3, s10, 7
	s_and_b32 s30, s2, 31
	s_lshl_b32 s31, s3, 5
	s_or_b32 s31, s31, s30
	s_lshr_b32 s30, s10, 8
	s_cmp_eq_u32 s8, 0x100
	s_cselect_b32 s2, s31, s2
	s_cselect_b32 s17, s30, s3
	s_lshl_b32 s16, s2, 8
	s_cmp_lt_u32 s2, 0x80
	s_cselect_b32 s12, s82, s83
	s_cselect_b32 s13, 10, 8
	s_cselect_b32 s49, 12, 10
	s_cselect_b32 s3, s84, s85
	s_and_b32 s3, s16, s3
	s_sub_i32 s15, s16, s3
	s_lshl_b32 s30, 1, s13
	s_add_i32 s14, s30, -1
	s_lshl_b32 s30, s17, 23
	s_lshl_b32 s3, s3, 7
	s_add_u32 s30, s30, s3
	s_add_u32 s18, s4, s30
	s_addc_u32 s19, s5, 0
	s_add_u32 s20, s18, 0x4000000
	s_addc_u32 s21, s19, 0
	s_add_u32 s22, s18, 0x8000000
	s_addc_u32 s23, s19, 0
	s_lshr_b32 s28, s11, 1
	s_lshl_b32 s24, s28, 1
	s_and_b32 s2, s11, 1
	s_lshl_b32 s2, s2, 3
	s_add_i32 s2, s2, s0
	s_and_b32 s3, s2, 3
	s_lshr_b32 s30, s2, 2
	s_cmp_eq_u32 s28, 1
	s_cselect_b32 s25, s3, s2
	s_cselect_b32 s30, s30, 0
	s_cmp_eq_u32 s28, 0
	s_cselect_b32 s25, 0, s25
	s_cselect_b32 s30, s2, s30
	s_lshr_b32 s3, s15, s24
	s_lshl_b32 s30, s30, 4
	s_add_i32 s26, s3, s30
	s_lshr_b32 s27, s12, s24
	s_cmp_lt_u32 s26, 64
	s_cselect_b32 s2, 1, 0
	s_add_i32 s3, s26, 0x50
	s_cmp_gt_u32 s3, s27
	s_cselect_b32 s3, 1, 0
	s_or_b32 s29, s2, s3
	s_lshl_b32 s41, 1, s24
	s_lshl_b32 s42, 2, s24
	s_lshl_b32 s43, 3, s24
	s_lshl_b32 s44, 4, s24
	s_lshl_b32 s45, 5, s24
	s_lshl_b32 s46, 6, s24
	s_lshl_b32 s47, 7, s24
	s_lshl_b32 s48, 8, s24
	v_add_u32_e32 v179, s26, v160
	v_lshlrev_b32_e32 v179, s24, v179
	v_add_u32_e32 v179, s25, v179
	v_subrev_u32_e32 v182, s15, v179
	v_lshrrev_b32_e32 v183, 4, v182
	v_add_u32_e32 v183, v183, v182
	v_mad_u32_u24 v176, v183, s79, v161
	v_lshl_add_u32 v177, v182, 2, s80
	s_sub_i32 s2, s26, 64
	v_add_u32_e32 v178, s2, v169
	v_and_b32_e32 v182, 3, v179
	v_lshlrev_b32_e32 v182, s49, v182
	v_lshrrev_b32_e32 v183, 2, v179
	v_add_u32_e32 v182, v182, v183
	v_lshl_add_u32 v182, v182, 7, v161
	global_load_dwordx4 v[72:75], v182, s[18:19]
	global_load_dwordx4 v[76:79], v182, s[18:19] offset:64
	s_lshl_b32 s2, 64, s24
	v_subrev_u32_e32 v179, s2, v179
	v_and_b32_e32 v147, 3, v179
	v_lshlrev_b32_e32 v147, s49, v147
	v_bfe_u32 v182, v179, 2, 2
	v_add_u32_e32 v147, v147, v182
	v_lshl_add_u32 v147, v147, 7, v161
	v_ashrrev_i32_e32 v179, 4, v179
	v_med3_i32 v183, v179, 0, s14
	v_lshl_add_u32 v183, v183, 9, v147
	global_load_dwordx4 v[0:3], v183, s[20:21]
	global_load_dwordx4 v[4:7], v183, s[20:21] offset:64
	v_add_u32_e32 v182, s41, v179
	v_med3_i32 v182, v182, 0, s14
	v_lshl_add_u32 v182, v182, 9, v147
	global_load_dwordx4 v[8:11], v182, s[20:21]
	global_load_dwordx4 v[12:15], v182, s[20:21] offset:64
	v_add_u32_e32 v183, s42, v179
	v_med3_i32 v183, v183, 0, s14
	v_lshl_add_u32 v183, v183, 9, v147
	global_load_dwordx4 v[16:19], v183, s[20:21]
	global_load_dwordx4 v[20:23], v183, s[20:21] offset:64
	v_add_u32_e32 v182, s43, v179
	v_med3_i32 v182, v182, 0, s14
	v_lshl_add_u32 v182, v182, 9, v147
	global_load_dwordx4 v[24:27], v182, s[20:21]
	global_load_dwordx4 v[28:31], v182, s[20:21] offset:64
	v_add_u32_e32 v183, s44, v179
	v_med3_i32 v183, v183, 0, s14
	v_lshl_add_u32 v183, v183, 9, v147
	global_load_dwordx4 v[32:35], v183, s[20:21]
	global_load_dwordx4 v[36:39], v183, s[20:21] offset:64
	v_add_u32_e32 v182, s45, v179
	v_med3_i32 v182, v182, 0, s14
	v_lshl_add_u32 v182, v182, 9, v147
	global_load_dwordx4 v[40:43], v182, s[20:21]
	global_load_dwordx4 v[44:47], v182, s[20:21] offset:64
	v_add_u32_e32 v183, s46, v179
	v_med3_i32 v183, v183, 0, s14
	v_lshl_add_u32 v183, v183, 9, v147
	global_load_dwordx4 v[48:51], v183, s[20:21]
	global_load_dwordx4 v[52:55], v183, s[20:21] offset:64
	v_add_u32_e32 v182, s47, v179
	v_med3_i32 v182, v182, 0, s14
	v_lshl_add_u32 v182, v182, 9, v147
	global_load_dwordx4 v[56:59], v182, s[20:21]
	global_load_dwordx4 v[60:63], v182, s[20:21] offset:64
	v_add_u32_e32 v183, s48, v179
	v_med3_i32 v183, v183, 0, s14
	v_lshl_add_u32 v183, v183, 9, v147
	global_load_dwordx4 v[64:67], v183, s[20:21]
	global_load_dwordx4 v[68:71], v183, s[20:21] offset:64
	s_add_i32 s2, s26, -64
	v_add_u32_e32 v179, s2, v164
	v_lshlrev_b32_e32 v179, s24, v179
	v_add_u32_e32 v179, s25, v179
	v_and_b32_e32 v147, 3, v179
	v_lshlrev_b32_e32 v147, s49, v147
	v_bfe_u32 v182, v179, 2, 2
	v_add_u32_e32 v147, v147, v182
	v_lshl_add_u32 v147, v147, 7, v162
	v_ashrrev_i32_e32 v179, 4, v179
	v_med3_i32 v183, v179, 0, s14
	v_lshl_add_u32 v183, v183, 9, v147
	global_load_dwordx4 v[80:83], v183, s[22:23]
	v_add_u32_e32 v182, s42, v179
	v_med3_i32 v182, v182, 0, s14
	v_lshl_add_u32 v182, v182, 9, v147
	global_load_dwordx4 v[96:99], v182, s[22:23]
	v_add_u32_e32 v183, s44, v179
	v_med3_i32 v183, v183, 0, s14
	v_lshl_add_u32 v183, v183, 9, v147
	global_load_dwordx4 v[112:115], v183, s[22:23]
	v_add_u32_e32 v182, s46, v179
	v_med3_i32 v182, v182, 0, s14
	v_lshl_add_u32 v182, v182, 9, v147
	global_load_dwordx4 v[128:131], v182, s[22:23]
	v_add_u32_e32 v183, s48, v179
	v_med3_i32 v183, v183, 0, s14
	v_lshl_add_u32 v183, v183, 9, v147
	global_load_dwordx4 v[152:155], v183, s[22:23]
	s_add_i32 s2, s26, -56
	v_add_u32_e32 v179, s2, v164
	v_lshlrev_b32_e32 v179, s24, v179
	v_add_u32_e32 v179, s25, v179
	v_and_b32_e32 v147, 3, v179
	v_lshlrev_b32_e32 v147, s49, v147
	v_bfe_u32 v182, v179, 2, 2
	v_add_u32_e32 v147, v147, v182
	v_lshl_add_u32 v147, v147, 7, v162
	v_ashrrev_i32_e32 v179, 4, v179
	v_med3_i32 v183, v179, 0, s14
	v_lshl_add_u32 v183, v183, 9, v147
	global_load_dwordx4 v[84:87], v183, s[22:23]
	v_add_u32_e32 v182, s42, v179
	v_med3_i32 v182, v182, 0, s14
	v_lshl_add_u32 v182, v182, 9, v147
	global_load_dwordx4 v[100:103], v182, s[22:23]
	v_add_u32_e32 v183, s44, v179
	v_med3_i32 v183, v183, 0, s14
	v_lshl_add_u32 v183, v183, 9, v147
	global_load_dwordx4 v[116:119], v183, s[22:23]
	v_add_u32_e32 v182, s46, v179
	v_med3_i32 v182, v182, 0, s14
	v_lshl_add_u32 v182, v182, 9, v147
	global_load_dwordx4 v[132:135], v182, s[22:23]
	v_add_u32_e32 v183, s48, v179
	v_med3_i32 v183, v183, 0, s14
	v_lshl_add_u32 v183, v183, 9, v147
	global_load_dwordx4 v[156:159], v183, s[22:23]
	s_add_i32 s2, s26, -48
	v_add_u32_e32 v179, s2, v164
	v_lshlrev_b32_e32 v179, s24, v179
	v_add_u32_e32 v179, s25, v179
	v_and_b32_e32 v147, 3, v179
	v_lshlrev_b32_e32 v147, s49, v147
	v_bfe_u32 v182, v179, 2, 2
	v_add_u32_e32 v147, v147, v182
	v_lshl_add_u32 v147, v147, 7, v162
	v_ashrrev_i32_e32 v179, 4, v179
	v_med3_i32 v183, v179, 0, s14
	v_lshl_add_u32 v183, v183, 9, v147
	global_load_dwordx4 v[88:91], v183, s[22:23]
	v_add_u32_e32 v182, s42, v179
	v_med3_i32 v182, v182, 0, s14
	v_lshl_add_u32 v182, v182, 9, v147
	global_load_dwordx4 v[104:107], v182, s[22:23]
	v_add_u32_e32 v183, s44, v179
	v_med3_i32 v183, v183, 0, s14
	v_lshl_add_u32 v183, v183, 9, v147
	global_load_dwordx4 v[120:123], v183, s[22:23]
	v_add_u32_e32 v182, s46, v179
	v_med3_i32 v182, v182, 0, s14
	v_lshl_add_u32 v182, v182, 9, v147
	global_load_dwordx4 v[136:139], v182, s[22:23]
	s_add_i32 s2, s26, -40
	v_add_u32_e32 v179, s2, v164
	v_lshlrev_b32_e32 v179, s24, v179
	v_add_u32_e32 v179, s25, v179
	v_and_b32_e32 v147, 3, v179
	v_lshlrev_b32_e32 v147, s49, v147
	v_bfe_u32 v182, v179, 2, 2
	v_add_u32_e32 v147, v147, v182
	v_lshl_add_u32 v147, v147, 7, v162
	v_ashrrev_i32_e32 v179, 4, v179
	v_med3_i32 v183, v179, 0, s14
	v_lshl_add_u32 v183, v183, 9, v147
	global_load_dwordx4 v[92:95], v183, s[22:23]
	v_add_u32_e32 v182, s42, v179
	v_med3_i32 v182, v182, 0, s14
	v_lshl_add_u32 v182, v182, 9, v147
	global_load_dwordx4 v[108:111], v182, s[22:23]
	v_add_u32_e32 v183, s44, v179
	v_med3_i32 v183, v183, 0, s14
	v_lshl_add_u32 v183, v183, 9, v147
	global_load_dwordx4 v[124:127], v183, s[22:23]
	v_add_u32_e32 v182, s46, v179
	v_med3_i32 v182, v182, 0, s14
	v_lshl_add_u32 v182, v182, 9, v147
	global_load_dwordx4 v[140:143], v182, s[22:23]
.Latt_loop:
	s_mov_b32 s33, s27
	s_mov_b32 s34, s28
	s_mov_b32 s35, s29
	s_mov_b32 s36, s11
	s_mov_b32 s37, s16
	s_mov_b32 s38, s17
	v_mov_b32_e32 v173, v176
	v_mov_b32_e32 v174, v177
	v_mov_b32_e32 v175, v178
	s_add_i32 s11, s11, 1
	s_cmp_lt_u32 s11, 6
	s_cbranch_scc1 .Latt_tp
	s_add_i32 s86, s10, s8
	s_cmp_lt_u32 s86, 0x800
	s_cbranch_scc1 .Latt_newunit
	s_mov_b32 s39, 1
	s_mov_b32 s11, 5
	s_branch .Latt_tp
.Latt_newunit:
	s_mov_b32 s10, s86
	s_mov_b32 s11, 0
	s_lshr_b32 s2, s10, 3
	s_and_b32 s3, s10, 7
	s_and_b32 s30, s2, 31
	s_lshl_b32 s31, s3, 5
	s_or_b32 s31, s31, s30
	s_lshr_b32 s30, s10, 8
	s_cmp_eq_u32 s8, 0x100
	s_cselect_b32 s2, s31, s2
	s_cselect_b32 s17, s30, s3
	s_lshl_b32 s16, s2, 8
	s_cmp_lt_u32 s2, 0x80
	s_cselect_b32 s12, s82, s83
	s_cselect_b32 s13, 10, 8
	s_cselect_b32 s49, 12, 10
	s_cselect_b32 s3, s84, s85
	s_and_b32 s3, s16, s3
	s_sub_i32 s15, s16, s3
	s_lshl_b32 s30, 1, s13
	s_add_i32 s14, s30, -1
	s_lshl_b32 s30, s17, 23
	s_lshl_b32 s3, s3, 7
	s_add_u32 s30, s30, s3
	s_add_u32 s18, s4, s30
	s_addc_u32 s19, s5, 0
	s_add_u32 s20, s18, 0x4000000
	s_addc_u32 s21, s19, 0
	s_add_u32 s22, s18, 0x8000000
	s_addc_u32 s23, s19, 0
.Latt_tp:
	s_lshr_b32 s28, s11, 1
	s_lshl_b32 s24, s28, 1
	s_and_b32 s2, s11, 1
	s_lshl_b32 s2, s2, 3
	s_add_i32 s2, s2, s0
	s_and_b32 s3, s2, 3
	s_lshr_b32 s30, s2, 2
	s_cmp_eq_u32 s28, 1
	s_cselect_b32 s25, s3, s2
	s_cselect_b32 s30, s30, 0
	s_cmp_eq_u32 s28, 0
	s_cselect_b32 s25, 0, s25
	s_cselect_b32 s30, s2, s30
	s_lshr_b32 s3, s15, s24
	s_lshl_b32 s30, s30, 4
	s_add_i32 s26, s3, s30
	s_lshr_b32 s27, s12, s24
	s_cmp_lt_u32 s26, 64
	s_cselect_b32 s2, 1, 0
	s_add_i32 s3, s26, 0x50
	s_cmp_gt_u32 s3, s27
	s_cselect_b32 s3, 1, 0
	s_or_b32 s29, s2, s3
	s_lshl_b32 s41, 1, s24
	s_lshl_b32 s42, 2, s24
	s_lshl_b32 s43, 3, s24
	s_lshl_b32 s44, 4, s24
	s_lshl_b32 s45, 5, s24
	s_lshl_b32 s46, 6, s24
	s_lshl_b32 s47, 7, s24
	s_lshl_b32 s48, 8, s24
	s_waitcnt vmcnt(18)
	s_cmp_eq_u32 s35, 0
	s_cbranch_scc0 .Latt_s_edge
	v_mov_b32_e32 v236, 0
	v_mfma_f32_16x16x32_bf16 v[220:223], v[0:3], v[72:75], 0
	v_mfma_f32_16x16x32_bf16 v[220:223], v[4:7], v[76:79], v[220:223]
	v_mfma_f32_16x16x32_bf16 v[224:227], v[8:11], v[72:75], 0
	v_mfma_f32_16x16x32_bf16 v[224:227], v[12:15], v[76:79], v[224:227]
	s_nop 5
	v_min_f32_e32 v228, 0x42a00000, v220
	v_min_f32_e32 v229, 0x42a00000, v221
	v_min_f32_e32 v230, 0x42a00000, v222
	v_min_f32_e32 v231, 0x42a00000, v223
	v_mfma_f32_16x16x32_bf16 v[220:223], v[16:19], v[72:75], 0
	v_mfma_f32_16x16x32_bf16 v[220:223], v[20:23], v[76:79], v[220:223]
	v_mul_f32_e32 v228, 0x3fb8aa3b, v228
	v_mul_f32_e32 v229, 0x3fb8aa3b, v229
	v_mul_f32_e32 v230, 0x3fb8aa3b, v230
	v_mul_f32_e32 v231, 0x3fb8aa3b, v231
	v_exp_f32_e32 v228, v228
	v_exp_f32_e32 v229, v229
	v_exp_f32_e32 v230, v230
	v_exp_f32_e32 v231, v231
	v_cndmask_b32_e64 v228, 0, v228, s[54:55]
	v_cndmask_b32_e64 v229, 0, v229, s[56:57]
	v_cndmask_b32_e64 v230, 0, v230, s[58:59]
	v_cndmask_b32_e64 v231, 0, v231, s[60:61]
	v_add_f32_e32 v236, v236, v228
	v_add_f32_e32 v236, v236, v229
	v_add_f32_e32 v236, v236, v230
	v_add_f32_e32 v236, v236, v231
	v_cvt_pk_bf16_f32 v184, v228, v229
	v_cvt_pk_bf16_f32 v185, v230, v231
	v_min_f32_e32 v232, 0x42a00000, v224
	v_min_f32_e32 v233, 0x42a00000, v225
	v_min_f32_e32 v234, 0x42a00000, v226
	v_min_f32_e32 v235, 0x42a00000, v227
	v_mfma_f32_16x16x32_bf16 v[224:227], v[24:27], v[72:75], 0
	v_mfma_f32_16x16x32_bf16 v[224:227], v[28:31], v[76:79], v[224:227]
	v_mul_f32_e32 v232, 0x3fb8aa3b, v232
	v_mul_f32_e32 v233, 0x3fb8aa3b, v233
	v_mul_f32_e32 v234, 0x3fb8aa3b, v234
	v_mul_f32_e32 v235, 0x3fb8aa3b, v235
	v_exp_f32_e32 v232, v232
	v_exp_f32_e32 v233, v233
	v_exp_f32_e32 v234, v234
	v_exp_f32_e32 v235, v235
	v_add_f32_e32 v236, v236, v232
	v_add_f32_e32 v236, v236, v233
	v_add_f32_e32 v236, v236, v234
	v_add_f32_e32 v236, v236, v235
	v_cvt_pk_bf16_f32 v186, v232, v233
	v_cvt_pk_bf16_f32 v187, v234, v235
	v_min_f32_e32 v228, 0x42a00000, v220
	v_min_f32_e32 v229, 0x42a00000, v221
	v_min_f32_e32 v230, 0x42a00000, v222
	v_min_f32_e32 v231, 0x42a00000, v223
	v_mfma_f32_16x16x32_bf16 v[220:223], v[32:35], v[72:75], 0
	v_mfma_f32_16x16x32_bf16 v[220:223], v[36:39], v[76:79], v[220:223]
	v_mul_f32_e32 v228, 0x3fb8aa3b, v228
	v_mul_f32_e32 v229, 0x3fb8aa3b, v229
	v_mul_f32_e32 v230, 0x3fb8aa3b, v230
	v_mul_f32_e32 v231, 0x3fb8aa3b, v231
	v_exp_f32_e32 v228, v228
	v_exp_f32_e32 v229, v229
	v_exp_f32_e32 v230, v230
	v_exp_f32_e32 v231, v231
	v_add_f32_e32 v236, v236, v228
	v_add_f32_e32 v236, v236, v229
	v_add_f32_e32 v236, v236, v230
	v_add_f32_e32 v236, v236, v231
	v_cvt_pk_bf16_f32 v188, v228, v229
	v_cvt_pk_bf16_f32 v189, v230, v231
	v_min_f32_e32 v232, 0x42a00000, v224
	v_min_f32_e32 v233, 0x42a00000, v225
	v_min_f32_e32 v234, 0x42a00000, v226
	v_min_f32_e32 v235, 0x42a00000, v227
	v_mfma_f32_16x16x32_bf16 v[224:227], v[40:43], v[72:75], 0
	v_mfma_f32_16x16x32_bf16 v[224:227], v[44:47], v[76:79], v[224:227]
	v_mul_f32_e32 v232, 0x3fb8aa3b, v232
	v_mul_f32_e32 v233, 0x3fb8aa3b, v233
	v_mul_f32_e32 v234, 0x3fb8aa3b, v234
	v_mul_f32_e32 v235, 0x3fb8aa3b, v235
	v_exp_f32_e32 v232, v232
	v_exp_f32_e32 v233, v233
	v_exp_f32_e32 v234, v234
	v_exp_f32_e32 v235, v235
	v_add_f32_e32 v236, v236, v232
	v_add_f32_e32 v236, v236, v233
	v_add_f32_e32 v236, v236, v234
	v_add_f32_e32 v236, v236, v235
	v_cvt_pk_bf16_f32 v190, v232, v233
	v_cvt_pk_bf16_f32 v191, v234, v235
	v_min_f32_e32 v228, 0x42a00000, v220
	v_min_f32_e32 v229, 0x42a00000, v221
	v_min_f32_e32 v230, 0x42a00000, v222
	v_min_f32_e32 v231, 0x42a00000, v223
	v_mfma_f32_16x16x32_bf16 v[220:223], v[48:51], v[72:75], 0
	v_mfma_f32_16x16x32_bf16 v[220:223], v[52:55], v[76:79], v[220:223]
	v_mul_f32_e32 v228, 0x3fb8aa3b, v228
	v_mul_f32_e32 v229, 0x3fb8aa3b, v229
	v_mul_f32_e32 v230, 0x3fb8aa3b, v230
	v_mul_f32_e32 v231, 0x3fb8aa3b, v231
	v_exp_f32_e32 v228, v228
	v_exp_f32_e32 v229, v229
	v_exp_f32_e32 v230, v230
	v_exp_f32_e32 v231, v231
	v_add_f32_e32 v236, v236, v228
	v_add_f32_e32 v236, v236, v229
	v_add_f32_e32 v236, v236, v230
	v_add_f32_e32 v236, v236, v231
	v_cvt_pk_bf16_f32 v192, v228, v229
	v_cvt_pk_bf16_f32 v193, v230, v231
	v_min_f32_e32 v232, 0x42a00000, v224
	v_min_f32_e32 v233, 0x42a00000, v225
	v_min_f32_e32 v234, 0x42a00000, v226
	v_min_f32_e32 v235, 0x42a00000, v227
	v_mfma_f32_16x16x32_bf16 v[224:227], v[56:59], v[72:75], 0
	v_mfma_f32_16x16x32_bf16 v[224:227], v[60:63], v[76:79], v[224:227]
	v_mul_f32_e32 v232, 0x3fb8aa3b, v232
	v_mul_f32_e32 v233, 0x3fb8aa3b, v233
	v_mul_f32_e32 v234, 0x3fb8aa3b, v234
	v_mul_f32_e32 v235, 0x3fb8aa3b, v235
	v_exp_f32_e32 v232, v232
	v_exp_f32_e32 v233, v233
	v_exp_f32_e32 v234, v234
	v_exp_f32_e32 v235, v235
	v_add_f32_e32 v236, v236, v232
	v_add_f32_e32 v236, v236, v233
	v_add_f32_e32 v236, v236, v234
	v_add_f32_e32 v236, v236, v235
	v_cvt_pk_bf16_f32 v194, v232, v233
	v_cvt_pk_bf16_f32 v195, v234, v235
	v_min_f32_e32 v228, 0x42a00000, v220
	v_min_f32_e32 v229, 0x42a00000, v221
	v_min_f32_e32 v230, 0x42a00000, v222
	v_min_f32_e32 v231, 0x42a00000, v223
	v_mfma_f32_16x16x32_bf16 v[220:223], v[64:67], v[72:75], 0
	v_mfma_f32_16x16x32_bf16 v[220:223], v[68:71], v[76:79], v[220:223]
	v_mul_f32_e32 v228, 0x3fb8aa3b, v228
	v_mul_f32_e32 v229, 0x3fb8aa3b, v229
	v_mul_f32_e32 v230, 0x3fb8aa3b, v230
	v_mul_f32_e32 v231, 0x3fb8aa3b, v231
	v_exp_f32_e32 v228, v228
	v_exp_f32_e32 v229, v229
	v_exp_f32_e32 v230, v230
	v_exp_f32_e32 v231, v231
	v_add_f32_e32 v236, v236, v228
	v_add_f32_e32 v236, v236, v229
	v_add_f32_e32 v236, v236, v230
	v_add_f32_e32 v236, v236, v231
	v_cvt_pk_bf16_f32 v196, v228, v229
	v_cvt_pk_bf16_f32 v197, v230, v231
	v_min_f32_e32 v232, 0x42a00000, v224
	v_min_f32_e32 v233, 0x42a00000, v225
	v_min_f32_e32 v234, 0x42a00000, v226
	v_min_f32_e32 v235, 0x42a00000, v227
	v_mul_f32_e32 v232, 0x3fb8aa3b, v232
	v_mul_f32_e32 v233, 0x3fb8aa3b, v233
	v_mul_f32_e32 v234, 0x3fb8aa3b, v234
	v_mul_f32_e32 v235, 0x3fb8aa3b, v235
	v_exp_f32_e32 v232, v232
	v_exp_f32_e32 v233, v233
	v_exp_f32_e32 v234, v234
	v_exp_f32_e32 v235, v235
	v_add_f32_e32 v236, v236, v232
	v_add_f32_e32 v236, v236, v233
	v_add_f32_e32 v236, v236, v234
	v_add_f32_e32 v236, v236, v235
	v_cvt_pk_bf16_f32 v198, v232, v233
	v_cvt_pk_bf16_f32 v199, v234, v235
	v_min_f32_e32 v228, 0x42a00000, v220
	v_min_f32_e32 v229, 0x42a00000, v221
	v_min_f32_e32 v230, 0x42a00000, v222
	v_min_f32_e32 v231, 0x42a00000, v223
	v_mul_f32_e32 v228, 0x3fb8aa3b, v228
	v_mul_f32_e32 v229, 0x3fb8aa3b, v229
	v_mul_f32_e32 v230, 0x3fb8aa3b, v230
	v_mul_f32_e32 v231, 0x3fb8aa3b, v231
	v_exp_f32_e32 v228, v228
	v_exp_f32_e32 v229, v229
	v_exp_f32_e32 v230, v230
	v_exp_f32_e32 v231, v231
	v_cndmask_b32_e64 v228, 0, v228, s[62:63]
	v_cndmask_b32_e64 v229, 0, v229, s[64:65]
	v_cndmask_b32_e64 v230, 0, v230, s[66:67]
	v_cndmask_b32_e64 v231, 0, v231, s[68:69]
	v_add_f32_e32 v236, v236, v228
	v_add_f32_e32 v236, v236, v229
	v_add_f32_e32 v236, v236, v230
	v_add_f32_e32 v236, v236, v231
	v_cvt_pk_bf16_f32 v200, v228, v229
	v_cvt_pk_bf16_f32 v201, v230, v231
	s_branch .Latt_s_done
.Latt_s_edge:
	v_mov_b32_e32 v236, 0
	v_mfma_f32_16x16x32_bf16 v[220:223], v[0:3], v[72:75], 0
	v_mfma_f32_16x16x32_bf16 v[220:223], v[4:7], v[76:79], v[220:223]
	v_mfma_f32_16x16x32_bf16 v[224:227], v[8:11], v[72:75], 0
	v_mfma_f32_16x16x32_bf16 v[224:227], v[12:15], v[76:79], v[224:227]
	s_nop 5
	v_min_f32_e32 v228, 0x42a00000, v220
	v_min_f32_e32 v229, 0x42a00000, v221
	v_min_f32_e32 v230, 0x42a00000, v222
	v_min_f32_e32 v231, 0x42a00000, v223
	v_mfma_f32_16x16x32_bf16 v[220:223], v[16:19], v[72:75], 0
	v_mfma_f32_16x16x32_bf16 v[220:223], v[20:23], v[76:79], v[220:223]
	v_mul_f32_e32 v228, 0x3fb8aa3b, v228
	v_mul_f32_e32 v229, 0x3fb8aa3b, v229
	v_mul_f32_e32 v230, 0x3fb8aa3b, v230
	v_mul_f32_e32 v231, 0x3fb8aa3b, v231
	v_exp_f32_e32 v228, v228
	v_exp_f32_e32 v229, v229
	v_exp_f32_e32 v230, v230
	v_exp_f32_e32 v231, v231
	v_mov_b32_e32 v237, v175
	v_add_u32_e32 v238, 1, v175
	v_add_u32_e32 v239, 2, v175
	v_add_u32_e32 v240, 3, v175
	v_cmp_gt_u32_e64 s[70:71], s33, v237
	v_cmp_gt_u32_e64 s[72:73], s33, v238
	v_cmp_gt_u32_e64 s[74:75], s33, v239
	v_cmp_gt_u32_e64 s[76:77], s33, v240
	v_cndmask_b32_e64 v228, 0, v228, s[54:55]
	v_cndmask_b32_e64 v229, 0, v229, s[56:57]
	v_cndmask_b32_e64 v230, 0, v230, s[58:59]
	v_cndmask_b32_e64 v231, 0, v231, s[60:61]
	v_cndmask_b32_e64 v228, 0, v228, s[70:71]
	v_cndmask_b32_e64 v229, 0, v229, s[72:73]
	v_cndmask_b32_e64 v230, 0, v230, s[74:75]
	v_cndmask_b32_e64 v231, 0, v231, s[76:77]
	v_add_f32_e32 v236, v236, v228
	v_add_f32_e32 v236, v236, v229
	v_add_f32_e32 v236, v236, v230
	v_add_f32_e32 v236, v236, v231
	v_cvt_pk_bf16_f32 v184, v228, v229
	v_cvt_pk_bf16_f32 v185, v230, v231
	v_min_f32_e32 v232, 0x42a00000, v224
	v_min_f32_e32 v233, 0x42a00000, v225
	v_min_f32_e32 v234, 0x42a00000, v226
	v_min_f32_e32 v235, 0x42a00000, v227
	v_mfma_f32_16x16x32_bf16 v[224:227], v[24:27], v[72:75], 0
	v_mfma_f32_16x16x32_bf16 v[224:227], v[28:31], v[76:79], v[224:227]
	v_mul_f32_e32 v232, 0x3fb8aa3b, v232
	v_mul_f32_e32 v233, 0x3fb8aa3b, v233
	v_mul_f32_e32 v234, 0x3fb8aa3b, v234
	v_mul_f32_e32 v235, 0x3fb8aa3b, v235
	v_exp_f32_e32 v232, v232
	v_exp_f32_e32 v233, v233
	v_exp_f32_e32 v234, v234
	v_exp_f32_e32 v235, v235
	v_add_u32_e32 v237, 16, v175
	v_add_u32_e32 v238, 17, v175
	v_add_u32_e32 v239, 18, v175
	v_add_u32_e32 v240, 19, v175
	v_cmp_gt_u32_e64 s[70:71], s33, v237
	v_cmp_gt_u32_e64 s[72:73], s33, v238
	v_cmp_gt_u32_e64 s[74:75], s33, v239
	v_cmp_gt_u32_e64 s[76:77], s33, v240
	v_cndmask_b32_e64 v232, 0, v232, s[70:71]
	v_cndmask_b32_e64 v233, 0, v233, s[72:73]
	v_cndmask_b32_e64 v234, 0, v234, s[74:75]
	v_cndmask_b32_e64 v235, 0, v235, s[76:77]
	v_add_f32_e32 v236, v236, v232
	v_add_f32_e32 v236, v236, v233
	v_add_f32_e32 v236, v236, v234
	v_add_f32_e32 v236, v236, v235
	v_cvt_pk_bf16_f32 v186, v232, v233
	v_cvt_pk_bf16_f32 v187, v234, v235
	v_min_f32_e32 v228, 0x42a00000, v220
	v_min_f32_e32 v229, 0x42a00000, v221
	v_min_f32_e32 v230, 0x42a00000, v222
	v_min_f32_e32 v231, 0x42a00000, v223
	v_mfma_f32_16x16x32_bf16 v[220:223], v[32:35], v[72:75], 0
	v_mfma_f32_16x16x32_bf16 v[220:223], v[36:39], v[76:79], v[220:223]
	v_mul_f32_e32 v228, 0x3fb8aa3b, v228
	v_mul_f32_e32 v229, 0x3fb8aa3b, v229
	v_mul_f32_e32 v230, 0x3fb8aa3b, v230
	v_mul_f32_e32 v231, 0x3fb8aa3b, v231
	v_exp_f32_e32 v228, v228
	v_exp_f32_e32 v229, v229
	v_exp_f32_e32 v230, v230
	v_exp_f32_e32 v231, v231
	v_add_u32_e32 v237, 32, v175
	v_add_u32_e32 v238, 33, v175
	v_add_u32_e32 v239, 34, v175
	v_add_u32_e32 v240, 35, v175
	v_cmp_gt_u32_e64 s[70:71], s33, v237
	v_cmp_gt_u32_e64 s[72:73], s33, v238
	v_cmp_gt_u32_e64 s[74:75], s33, v239
	v_cmp_gt_u32_e64 s[76:77], s33, v240
	v_cndmask_b32_e64 v228, 0, v228, s[70:71]
	v_cndmask_b32_e64 v229, 0, v229, s[72:73]
	v_cndmask_b32_e64 v230, 0, v230, s[74:75]
	v_cndmask_b32_e64 v231, 0, v231, s[76:77]
	v_add_f32_e32 v236, v236, v228
	v_add_f32_e32 v236, v236, v229
	v_add_f32_e32 v236, v236, v230
	v_add_f32_e32 v236, v236, v231
	v_cvt_pk_bf16_f32 v188, v228, v229
	v_cvt_pk_bf16_f32 v189, v230, v231
	v_min_f32_e32 v232, 0x42a00000, v224
	v_min_f32_e32 v233, 0x42a00000, v225
	v_min_f32_e32 v234, 0x42a00000, v226
	v_min_f32_e32 v235, 0x42a00000, v227
	v_mfma_f32_16x16x32_bf16 v[224:227], v[40:43], v[72:75], 0
	v_mfma_f32_16x16x32_bf16 v[224:227], v[44:47], v[76:79], v[224:227]
	v_mul_f32_e32 v232, 0x3fb8aa3b, v232
	v_mul_f32_e32 v233, 0x3fb8aa3b, v233
	v_mul_f32_e32 v234, 0x3fb8aa3b, v234
	v_mul_f32_e32 v235, 0x3fb8aa3b, v235
	v_exp_f32_e32 v232, v232
	v_exp_f32_e32 v233, v233
	v_exp_f32_e32 v234, v234
	v_exp_f32_e32 v235, v235
	v_add_u32_e32 v237, 48, v175
	v_add_u32_e32 v238, 49, v175
	v_add_u32_e32 v239, 50, v175
	v_add_u32_e32 v240, 51, v175
	v_cmp_gt_u32_e64 s[70:71], s33, v237
	v_cmp_gt_u32_e64 s[72:73], s33, v238
	v_cmp_gt_u32_e64 s[74:75], s33, v239
	v_cmp_gt_u32_e64 s[76:77], s33, v240
	v_cndmask_b32_e64 v232, 0, v232, s[70:71]
	v_cndmask_b32_e64 v233, 0, v233, s[72:73]
	v_cndmask_b32_e64 v234, 0, v234, s[74:75]
	v_cndmask_b32_e64 v235, 0, v235, s[76:77]
	v_add_f32_e32 v236, v236, v232
	v_add_f32_e32 v236, v236, v233
	v_add_f32_e32 v236, v236, v234
	v_add_f32_e32 v236, v236, v235
	v_cvt_pk_bf16_f32 v190, v232, v233
	v_cvt_pk_bf16_f32 v191, v234, v235
	v_min_f32_e32 v228, 0x42a00000, v220
	v_min_f32_e32 v229, 0x42a00000, v221
	v_min_f32_e32 v230, 0x42a00000, v222
	v_min_f32_e32 v231, 0x42a00000, v223
	v_mfma_f32_16x16x32_bf16 v[220:223], v[48:51], v[72:75], 0
	v_mfma_f32_16x16x32_bf16 v[220:223], v[52:55], v[76:79], v[220:223]
	v_mul_f32_e32 v228, 0x3fb8aa3b, v228
	v_mul_f32_e32 v229, 0x3fb8aa3b, v229
	v_mul_f32_e32 v230, 0x3fb8aa3b, v230
	v_mul_f32_e32 v231, 0x3fb8aa3b, v231
	v_exp_f32_e32 v228, v228
	v_exp_f32_e32 v229, v229
	v_exp_f32_e32 v230, v230
	v_exp_f32_e32 v231, v231
	v_add_u32_e32 v237, 64, v175
	v_add_u32_e32 v238, 0x41, v175
	v_add_u32_e32 v239, 0x42, v175
	v_add_u32_e32 v240, 0x43, v175
	v_cmp_gt_u32_e64 s[70:71], s33, v237
	v_cmp_gt_u32_e64 s[72:73], s33, v238
	v_cmp_gt_u32_e64 s[74:75], s33, v239
	v_cmp_gt_u32_e64 s[76:77], s33, v240
	v_cndmask_b32_e64 v228, 0, v228, s[70:71]
	v_cndmask_b32_e64 v229, 0, v229, s[72:73]
	v_cndmask_b32_e64 v230, 0, v230, s[74:75]
	v_cndmask_b32_e64 v231, 0, v231, s[76:77]
	v_add_f32_e32 v236, v236, v228
	v_add_f32_e32 v236, v236, v229
	v_add_f32_e32 v236, v236, v230
	v_add_f32_e32 v236, v236, v231
	v_cvt_pk_bf16_f32 v192, v228, v229
	v_cvt_pk_bf16_f32 v193, v230, v231
	v_min_f32_e32 v232, 0x42a00000, v224
	v_min_f32_e32 v233, 0x42a00000, v225
	v_min_f32_e32 v234, 0x42a00000, v226
	v_min_f32_e32 v235, 0x42a00000, v227
	v_mfma_f32_16x16x32_bf16 v[224:227], v[56:59], v[72:75], 0
	v_mfma_f32_16x16x32_bf16 v[224:227], v[60:63], v[76:79], v[224:227]
	v_mul_f32_e32 v232, 0x3fb8aa3b, v232
	v_mul_f32_e32 v233, 0x3fb8aa3b, v233
	v_mul_f32_e32 v234, 0x3fb8aa3b, v234
	v_mul_f32_e32 v235, 0x3fb8aa3b, v235
	v_exp_f32_e32 v232, v232
	v_exp_f32_e32 v233, v233
	v_exp_f32_e32 v234, v234
	v_exp_f32_e32 v235, v235
	v_add_u32_e32 v237, 0x50, v175
	v_add_u32_e32 v238, 0x51, v175
	v_add_u32_e32 v239, 0x52, v175
	v_add_u32_e32 v240, 0x53, v175
	v_cmp_gt_u32_e64 s[70:71], s33, v237
	v_cmp_gt_u32_e64 s[72:73], s33, v238
	v_cmp_gt_u32_e64 s[74:75], s33, v239
	v_cmp_gt_u32_e64 s[76:77], s33, v240
	v_cndmask_b32_e64 v232, 0, v232, s[70:71]
	v_cndmask_b32_e64 v233, 0, v233, s[72:73]
	v_cndmask_b32_e64 v234, 0, v234, s[74:75]
	v_cndmask_b32_e64 v235, 0, v235, s[76:77]
	v_add_f32_e32 v236, v236, v232
	v_add_f32_e32 v236, v236, v233
	v_add_f32_e32 v236, v236, v234
	v_add_f32_e32 v236, v236, v235
	v_cvt_pk_bf16_f32 v194, v232, v233
	v_cvt_pk_bf16_f32 v195, v234, v235
	v_min_f32_e32 v228, 0x42a00000, v220
	v_min_f32_e32 v229, 0x42a00000, v221
	v_min_f32_e32 v230, 0x42a00000, v222
	v_min_f32_e32 v231, 0x42a00000, v223
	v_mfma_f32_16x16x32_bf16 v[220:223], v[64:67], v[72:75], 0
	v_mfma_f32_16x16x32_bf16 v[220:223], v[68:71], v[76:79], v[220:223]
	v_mul_f32_e32 v228, 0x3fb8aa3b, v228
	v_mul_f32_e32 v229, 0x3fb8aa3b, v229
	v_mul_f32_e32 v230, 0x3fb8aa3b, v230
	v_mul_f32_e32 v231, 0x3fb8aa3b, v231
	v_exp_f32_e32 v228, v228
	v_exp_f32_e32 v229, v229
	v_exp_f32_e32 v230, v230
	v_exp_f32_e32 v231, v231
	v_add_u32_e32 v237, 0x60, v175
	v_add_u32_e32 v238, 0x61, v175
	v_add_u32_e32 v239, 0x62, v175
	v_add_u32_e32 v240, 0x63, v175
	v_cmp_gt_u32_e64 s[70:71], s33, v237
	v_cmp_gt_u32_e64 s[72:73], s33, v238
	v_cmp_gt_u32_e64 s[74:75], s33, v239
	v_cmp_gt_u32_e64 s[76:77], s33, v240
	v_cndmask_b32_e64 v228, 0, v228, s[70:71]
	v_cndmask_b32_e64 v229, 0, v229, s[72:73]
	v_cndmask_b32_e64 v230, 0, v230, s[74:75]
	v_cndmask_b32_e64 v231, 0, v231, s[76:77]
	v_add_f32_e32 v236, v236, v228
	v_add_f32_e32 v236, v236, v229
	v_add_f32_e32 v236, v236, v230
	v_add_f32_e32 v236, v236, v231
	v_cvt_pk_bf16_f32 v196, v228, v229
	v_cvt_pk_bf16_f32 v197, v230, v231
	v_min_f32_e32 v232, 0x42a00000, v224
	v_min_f32_e32 v233, 0x42a00000, v225
	v_min_f32_e32 v234, 0x42a00000, v226
	v_min_f32_e32 v235, 0x42a00000, v227
	v_mul_f32_e32 v232, 0x3fb8aa3b, v232
	v_mul_f32_e32 v233, 0x3fb8aa3b, v233
	v_mul_f32_e32 v234, 0x3fb8aa3b, v234
	v_mul_f32_e32 v235, 0x3fb8aa3b, v235
	v_exp_f32_e32 v232, v232
	v_exp_f32_e32 v233, v233
	v_exp_f32_e32 v234, v234
	v_exp_f32_e32 v235, v235
	v_add_u32_e32 v237, 0x70, v175
	v_add_u32_e32 v238, 0x71, v175
	v_add_u32_e32 v239, 0x72, v175
	v_add_u32_e32 v240, 0x73, v175
	v_cmp_gt_u32_e64 s[70:71], s33, v237
	v_cmp_gt_u32_e64 s[72:73], s33, v238
	v_cmp_gt_u32_e64 s[74:75], s33, v239
	v_cmp_gt_u32_e64 s[76:77], s33, v240
	v_cndmask_b32_e64 v232, 0, v232, s[70:71]
	v_cndmask_b32_e64 v233, 0, v233, s[72:73]
	v_cndmask_b32_e64 v234, 0, v234, s[74:75]
	v_cndmask_b32_e64 v235, 0, v235, s[76:77]
	v_add_f32_e32 v236, v236, v232
	v_add_f32_e32 v236, v236, v233
	v_add_f32_e32 v236, v236, v234
	v_add_f32_e32 v236, v236, v235
	v_cvt_pk_bf16_f32 v198, v232, v233
	v_cvt_pk_bf16_f32 v199, v234, v235
	v_min_f32_e32 v228, 0x42a00000, v220
	v_min_f32_e32 v229, 0x42a00000, v221
	v_min_f32_e32 v230, 0x42a00000, v222
	v_min_f32_e32 v231, 0x42a00000, v223
	v_mul_f32_e32 v228, 0x3fb8aa3b, v228
	v_mul_f32_e32 v229, 0x3fb8aa3b, v229
	v_mul_f32_e32 v230, 0x3fb8aa3b, v230
	v_mul_f32_e32 v231, 0x3fb8aa3b, v231
	v_exp_f32_e32 v228, v228
	v_exp_f32_e32 v229, v229
	v_exp_f32_e32 v230, v230
	v_exp_f32_e32 v231, v231
	v_add_u32_e32 v237, 0x80, v175
	v_add_u32_e32 v238, 0x81, v175
	v_add_u32_e32 v239, 0x82, v175
	v_add_u32_e32 v240, 0x83, v175
	v_cmp_gt_u32_e64 s[70:71], s33, v237
	v_cmp_gt_u32_e64 s[72:73], s33, v238
	v_cmp_gt_u32_e64 s[74:75], s33, v239
	v_cmp_gt_u32_e64 s[76:77], s33, v240
	v_cndmask_b32_e64 v228, 0, v228, s[62:63]
	v_cndmask_b32_e64 v229, 0, v229, s[64:65]
	v_cndmask_b32_e64 v230, 0, v230, s[66:67]
	v_cndmask_b32_e64 v231, 0, v231, s[68:69]
	v_cndmask_b32_e64 v228, 0, v228, s[70:71]
	v_cndmask_b32_e64 v229, 0, v229, s[72:73]
	v_cndmask_b32_e64 v230, 0, v230, s[74:75]
	v_cndmask_b32_e64 v231, 0, v231, s[76:77]
	v_add_f32_e32 v236, v236, v228
	v_add_f32_e32 v236, v236, v229
	v_add_f32_e32 v236, v236, v230
	v_add_f32_e32 v236, v236, v231
	v_cvt_pk_bf16_f32 v200, v228, v229
	v_cvt_pk_bf16_f32 v201, v230, v231
.Latt_s_done:
	ds_bpermute_b32 v241, v167, v236
	v_add_u32_e32 v179, s26, v160
	v_lshlrev_b32_e32 v179, s24, v179
	v_add_u32_e32 v179, s25, v179
	v_subrev_u32_e32 v182, s15, v179
	v_lshrrev_b32_e32 v183, 4, v182
	v_add_u32_e32 v183, v183, v182
	v_mad_u32_u24 v176, v183, s79, v161
	v_lshl_add_u32 v177, v182, 2, s80
	s_sub_i32 s2, s26, 64
	v_add_u32_e32 v178, s2, v169
	v_and_b32_e32 v182, 3, v179
	v_lshlrev_b32_e32 v182, s49, v182
	v_lshrrev_b32_e32 v183, 2, v179
	v_add_u32_e32 v182, v182, v183
	v_lshl_add_u32 v182, v182, 7, v161
	global_load_dwordx4 v[72:75], v182, s[18:19]
	global_load_dwordx4 v[76:79], v182, s[18:19] offset:64
	s_lshl_b32 s2, 64, s24
	v_subrev_u32_e32 v179, s2, v179
	v_and_b32_e32 v147, 3, v179
	v_lshlrev_b32_e32 v147, s49, v147
	v_bfe_u32 v182, v179, 2, 2
	v_add_u32_e32 v147, v147, v182
	v_lshl_add_u32 v147, v147, 7, v161
	v_ashrrev_i32_e32 v179, 4, v179
	v_med3_i32 v183, v179, 0, s14
	v_lshl_add_u32 v183, v183, 9, v147
	global_load_dwordx4 v[0:3], v183, s[20:21]
	global_load_dwordx4 v[4:7], v183, s[20:21] offset:64
	v_add_u32_e32 v182, s41, v179
	v_med3_i32 v182, v182, 0, s14
	v_lshl_add_u32 v182, v182, 9, v147
	global_load_dwordx4 v[8:11], v182, s[20:21]
	global_load_dwordx4 v[12:15], v182, s[20:21] offset:64
	v_add_u32_e32 v183, s42, v179
	v_med3_i32 v183, v183, 0, s14
	v_lshl_add_u32 v183, v183, 9, v147
	global_load_dwordx4 v[16:19], v183, s[20:21]
	global_load_dwordx4 v[20:23], v183, s[20:21] offset:64
	v_add_u32_e32 v182, s43, v179
	v_med3_i32 v182, v182, 0, s14
	v_lshl_add_u32 v182, v182, 9, v147
	global_load_dwordx4 v[24:27], v182, s[20:21]
	global_load_dwordx4 v[28:31], v182, s[20:21] offset:64
	v_add_u32_e32 v183, s44, v179
	v_med3_i32 v183, v183, 0, s14
	v_lshl_add_u32 v183, v183, 9, v147
	global_load_dwordx4 v[32:35], v183, s[20:21]
	global_load_dwordx4 v[36:39], v183, s[20:21] offset:64
	v_add_u32_e32 v182, s45, v179
	v_med3_i32 v182, v182, 0, s14
	v_lshl_add_u32 v182, v182, 9, v147
	global_load_dwordx4 v[40:43], v182, s[20:21]
	global_load_dwordx4 v[44:47], v182, s[20:21] offset:64
	v_add_u32_e32 v183, s46, v179
	v_med3_i32 v183, v183, 0, s14
	v_lshl_add_u32 v183, v183, 9, v147
	global_load_dwordx4 v[48:51], v183, s[20:21]
	global_load_dwordx4 v[52:55], v183, s[20:21] offset:64
	v_add_u32_e32 v182, s47, v179
	v_med3_i32 v182, v182, 0, s14
	v_lshl_add_u32 v182, v182, 9, v147
	global_load_dwordx4 v[56:59], v182, s[20:21]
	global_load_dwordx4 v[60:63], v182, s[20:21] offset:64
	v_add_u32_e32 v183, s48, v179
	v_med3_i32 v183, v183, 0, s14
	v_lshl_add_u32 v183, v183, 9, v147
	global_load_dwordx4 v[64:67], v183, s[20:21]
	global_load_dwordx4 v[68:71], v183, s[20:21] offset:64
	s_waitcnt lgkmcnt(0)
	v_add_f32_e32 v236, v236, v241
	ds_bpermute_b32 v241, v168, v236
	s_waitcnt vmcnt(20)
	s_waitcnt lgkmcnt(0)
	v_add_f32_e32 v236, v236, v241
	ds_write_b128 v165, v[80:83]
	ds_write_b128 v165, v[84:87] offset:1152
	ds_write_b128 v165, v[88:91] offset:2304
	ds_write_b128 v165, v[92:95] offset:3456
	s_waitcnt lgkmcnt(0)
	ds_read_b64_tr_b16 v[220:221], v166
	ds_read_b64_tr_b16 v[222:223], v166 offset:2304
	ds_read_b64_tr_b16 v[224:225], v166 offset:32
	ds_read_b64_tr_b16 v[226:227], v166 offset:2336
	ds_read_b64_tr_b16 v[228:229], v166 offset:64
	ds_read_b64_tr_b16 v[230:231], v166 offset:2368
	ds_read_b64_tr_b16 v[232:233], v166 offset:96
	ds_read_b64_tr_b16 v[234:235], v166 offset:2400
	s_waitcnt lgkmcnt(0)
	ds_write_b128 v165, v[96:99]
	ds_write_b128 v165, v[100:103] offset:1152
	ds_write_b128 v165, v[104:107] offset:2304
	ds_write_b128 v165, v[108:111] offset:3456
	v_mfma_f32_16x16x32_bf16 v[204:207], v[220:223], v[184:187], 0
	v_mfma_f32_16x16x32_bf16 v[208:211], v[224:227], v[184:187], 0
	v_mfma_f32_16x16x32_bf16 v[212:215], v[228:231], v[184:187], 0
	v_mfma_f32_16x16x32_bf16 v[216:219], v[232:235], v[184:187], 0
	s_waitcnt lgkmcnt(0)
	ds_read_b64_tr_b16 v[220:221], v166
	ds_read_b64_tr_b16 v[222:223], v166 offset:2304
	ds_read_b64_tr_b16 v[224:225], v166 offset:32
	ds_read_b64_tr_b16 v[226:227], v166 offset:2336
	ds_read_b64_tr_b16 v[228:229], v166 offset:64
	ds_read_b64_tr_b16 v[230:231], v166 offset:2368
	ds_read_b64_tr_b16 v[232:233], v166 offset:96
	ds_read_b64_tr_b16 v[234:235], v166 offset:2400
	s_waitcnt lgkmcnt(0)
	ds_write_b128 v165, v[112:115]
	ds_write_b128 v165, v[116:119] offset:1152
	ds_write_b128 v165, v[120:123] offset:2304
	ds_write_b128 v165, v[124:127] offset:3456
	v_mfma_f32_16x16x32_bf16 v[204:207], v[220:223], v[188:191], v[204:207]
	v_mfma_f32_16x16x32_bf16 v[208:211], v[224:227], v[188:191], v[208:211]
	v_mfma_f32_16x16x32_bf16 v[212:215], v[228:231], v[188:191], v[212:215]
	v_mfma_f32_16x16x32_bf16 v[216:219], v[232:235], v[188:191], v[216:219]
	s_waitcnt lgkmcnt(0)
	ds_read_b64_tr_b16 v[220:221], v166
	ds_read_b64_tr_b16 v[222:223], v166 offset:2304
	ds_read_b64_tr_b16 v[224:225], v166 offset:32
	ds_read_b64_tr_b16 v[226:227], v166 offset:2336
	ds_read_b64_tr_b16 v[228:229], v166 offset:64
	ds_read_b64_tr_b16 v[230:231], v166 offset:2368
	ds_read_b64_tr_b16 v[232:233], v166 offset:96
	ds_read_b64_tr_b16 v[234:235], v166 offset:2400
	s_waitcnt lgkmcnt(0)
	ds_write_b128 v165, v[128:131]
	ds_write_b128 v165, v[132:135] offset:1152
	ds_write_b128 v165, v[136:139] offset:2304
	ds_write_b128 v165, v[140:143] offset:3456
	v_mfma_f32_16x16x32_bf16 v[204:207], v[220:223], v[192:195], v[204:207]
	v_mfma_f32_16x16x32_bf16 v[208:211], v[224:227], v[192:195], v[208:211]
	v_mfma_f32_16x16x32_bf16 v[212:215], v[228:231], v[192:195], v[212:215]
	v_mfma_f32_16x16x32_bf16 v[216:219], v[232:235], v[192:195], v[216:219]
	s_waitcnt lgkmcnt(0)
	ds_read_b64_tr_b16 v[220:221], v166
	ds_read_b64_tr_b16 v[222:223], v166 offset:2304
	ds_read_b64_tr_b16 v[224:225], v166 offset:32
	ds_read_b64_tr_b16 v[226:227], v166 offset:2336
	ds_read_b64_tr_b16 v[228:229], v166 offset:64
	ds_read_b64_tr_b16 v[230:231], v166 offset:2368
	ds_read_b64_tr_b16 v[232:233], v166 offset:96
	ds_read_b64_tr_b16 v[234:235], v166 offset:2400
	s_waitcnt lgkmcnt(0)
	ds_write_b128 v165, v[152:155]
	ds_write_b128 v165, v[156:159] offset:1152
	v_mfma_f32_16x16x32_bf16 v[204:207], v[220:223], v[196:199], v[204:207]
	v_mfma_f32_16x16x32_bf16 v[208:211], v[224:227], v[196:199], v[208:211]
	v_mfma_f32_16x16x32_bf16 v[212:215], v[228:231], v[196:199], v[212:215]
	v_mfma_f32_16x16x32_bf16 v[216:219], v[232:235], v[196:199], v[216:219]
	s_waitcnt lgkmcnt(0)
	ds_read_b64_tr_b16 v[220:221], v166
	ds_read_b64_tr_b16 v[222:223], v166 offset:2304
	ds_read_b64_tr_b16 v[224:225], v166 offset:32
	ds_read_b64_tr_b16 v[226:227], v166 offset:2336
	ds_read_b64_tr_b16 v[228:229], v166 offset:64
	ds_read_b64_tr_b16 v[230:231], v166 offset:2368
	ds_read_b64_tr_b16 v[232:233], v166 offset:96
	ds_read_b64_tr_b16 v[234:235], v166 offset:2400
	s_waitcnt lgkmcnt(0)
	v_mfma_f32_16x16x32_bf16 v[204:207], v[220:223], v[200:203], v[204:207]
	v_mfma_f32_16x16x32_bf16 v[208:211], v[224:227], v[200:203], v[208:211]
	v_mfma_f32_16x16x32_bf16 v[212:215], v[228:231], v[200:203], v[212:215]
	v_mfma_f32_16x16x32_bf16 v[216:219], v[232:235], v[200:203], v[216:219]
	s_add_i32 s2, s26, -64
	v_add_u32_e32 v179, s2, v164
	v_lshlrev_b32_e32 v179, s24, v179
	v_add_u32_e32 v179, s25, v179
	v_and_b32_e32 v147, 3, v179
	v_lshlrev_b32_e32 v147, s49, v147
	v_bfe_u32 v182, v179, 2, 2
	v_add_u32_e32 v147, v147, v182
	v_lshl_add_u32 v147, v147, 7, v162
	v_ashrrev_i32_e32 v179, 4, v179
	v_med3_i32 v183, v179, 0, s14
	v_lshl_add_u32 v183, v183, 9, v147
	global_load_dwordx4 v[80:83], v183, s[22:23]
	v_add_u32_e32 v182, s42, v179
	v_med3_i32 v182, v182, 0, s14
	v_lshl_add_u32 v182, v182, 9, v147
	global_load_dwordx4 v[96:99], v182, s[22:23]
	v_add_u32_e32 v183, s44, v179
	v_med3_i32 v183, v183, 0, s14
	v_lshl_add_u32 v183, v183, 9, v147
	global_load_dwordx4 v[112:115], v183, s[22:23]
	v_add_u32_e32 v182, s46, v179
	v_med3_i32 v182, v182, 0, s14
	v_lshl_add_u32 v182, v182, 9, v147
	global_load_dwordx4 v[128:131], v182, s[22:23]
	v_add_u32_e32 v183, s48, v179
	v_med3_i32 v183, v183, 0, s14
	v_lshl_add_u32 v183, v183, 9, v147
	global_load_dwordx4 v[152:155], v183, s[22:23]
	s_add_i32 s2, s26, -56
	v_add_u32_e32 v179, s2, v164
	v_lshlrev_b32_e32 v179, s24, v179
	v_add_u32_e32 v179, s25, v179
	v_and_b32_e32 v147, 3, v179
	v_lshlrev_b32_e32 v147, s49, v147
	v_bfe_u32 v182, v179, 2, 2
	v_add_u32_e32 v147, v147, v182
	v_lshl_add_u32 v147, v147, 7, v162
	v_ashrrev_i32_e32 v179, 4, v179
	v_med3_i32 v183, v179, 0, s14
	v_lshl_add_u32 v183, v183, 9, v147
	global_load_dwordx4 v[84:87], v183, s[22:23]
	v_add_u32_e32 v182, s42, v179
	v_med3_i32 v182, v182, 0, s14
	v_lshl_add_u32 v182, v182, 9, v147
	global_load_dwordx4 v[100:103], v182, s[22:23]
	v_add_u32_e32 v183, s44, v179
	v_med3_i32 v183, v183, 0, s14
	v_lshl_add_u32 v183, v183, 9, v147
	global_load_dwordx4 v[116:119], v183, s[22:23]
	v_add_u32_e32 v182, s46, v179
	v_med3_i32 v182, v182, 0, s14
	v_lshl_add_u32 v182, v182, 9, v147
	global_load_dwordx4 v[132:135], v182, s[22:23]
	v_add_u32_e32 v183, s48, v179
	v_med3_i32 v183, v183, 0, s14
	v_lshl_add_u32 v183, v183, 9, v147
	global_load_dwordx4 v[156:159], v183, s[22:23]
	s_add_i32 s2, s26, -48
	v_add_u32_e32 v179, s2, v164
	v_lshlrev_b32_e32 v179, s24, v179
	v_add_u32_e32 v179, s25, v179
	v_and_b32_e32 v147, 3, v179
	v_lshlrev_b32_e32 v147, s49, v147
	v_bfe_u32 v182, v179, 2, 2
	v_add_u32_e32 v147, v147, v182
	v_lshl_add_u32 v147, v147, 7, v162
	v_ashrrev_i32_e32 v179, 4, v179
	v_med3_i32 v183, v179, 0, s14
	v_lshl_add_u32 v183, v183, 9, v147
	global_load_dwordx4 v[88:91], v183, s[22:23]
	v_add_u32_e32 v182, s42, v179
	v_med3_i32 v182, v182, 0, s14
	v_lshl_add_u32 v182, v182, 9, v147
	global_load_dwordx4 v[104:107], v182, s[22:23]
	v_add_u32_e32 v183, s44, v179
	v_med3_i32 v183, v183, 0, s14
	v_lshl_add_u32 v183, v183, 9, v147
	global_load_dwordx4 v[120:123], v183, s[22:23]
	v_add_u32_e32 v182, s46, v179
	v_med3_i32 v182, v182, 0, s14
	v_lshl_add_u32 v182, v182, 9, v147
	global_load_dwordx4 v[136:139], v182, s[22:23]
	s_add_i32 s2, s26, -40
	v_add_u32_e32 v179, s2, v164
	v_lshlrev_b32_e32 v179, s24, v179
	v_add_u32_e32 v179, s25, v179
	v_and_b32_e32 v147, 3, v179
	v_lshlrev_b32_e32 v147, s49, v147
	v_bfe_u32 v182, v179, 2, 2
	v_add_u32_e32 v147, v147, v182
	v_lshl_add_u32 v147, v147, 7, v162
	v_ashrrev_i32_e32 v179, 4, v179
	v_med3_i32 v183, v179, 0, s14
	v_lshl_add_u32 v183, v183, 9, v147
	global_load_dwordx4 v[92:95], v183, s[22:23]
	v_add_u32_e32 v182, s42, v179
	v_med3_i32 v182, v182, 0, s14
	v_lshl_add_u32 v182, v182, 9, v147
	global_load_dwordx4 v[108:111], v182, s[22:23]
	v_add_u32_e32 v183, s44, v179
	v_med3_i32 v183, v183, 0, s14
	v_lshl_add_u32 v183, v183, 9, v147
	global_load_dwordx4 v[124:127], v183, s[22:23]
	v_add_u32_e32 v182, s46, v179
	v_med3_i32 v182, v182, 0, s14
	v_lshl_add_u32 v182, v182, 9, v147
	global_load_dwordx4 v[140:143], v182, s[22:23]
	s_cmp_eq_u32 s34, 0
	s_cbranch_scc0 .Latt_acc_add
	ds_write_b128 v173, v[204:207]
	ds_write_b128 v173, v[208:211] offset:64
	ds_write_b128 v173, v[212:215] offset:128
	ds_write_b128 v173, v[216:219] offset:192
	ds_write_b32 v174, v236
	s_branch .Latt_acc_done
.Latt_acc_add:
	ds_read_b128 v[220:223], v173
	ds_read_b128 v[224:227], v173 offset:64
	ds_read_b128 v[228:231], v173 offset:128
	ds_read_b128 v[232:235], v173 offset:192
	ds_read_b32 v241, v174
	s_waitcnt lgkmcnt(0)
	v_add_f32_e32 v204, v220, v204
	v_add_f32_e32 v205, v221, v205
	v_add_f32_e32 v206, v222, v206
	v_add_f32_e32 v207, v223, v207
	v_add_f32_e32 v208, v224, v208
	v_add_f32_e32 v209, v225, v209
	v_add_f32_e32 v210, v226, v210
	v_add_f32_e32 v211, v227, v211
	v_add_f32_e32 v212, v228, v212
	v_add_f32_e32 v213, v229, v213
	v_add_f32_e32 v214, v230, v214
	v_add_f32_e32 v215, v231, v215
	v_add_f32_e32 v216, v232, v216
	v_add_f32_e32 v217, v233, v217
	v_add_f32_e32 v218, v234, v218
	v_add_f32_e32 v219, v235, v219
	v_add_f32_e32 v236, v241, v236
	ds_write_b128 v173, v[204:207]
	ds_write_b128 v173, v[208:211] offset:64
	ds_write_b128 v173, v[212:215] offset:128
	ds_write_b128 v173, v[216:219] offset:192
	ds_write_b32 v174, v236
.Latt_acc_done:
	s_and_b32 s2, s36, 1
	s_cmp_eq_u32 s2, 0
	s_cbranch_scc1 .Latt_nobar
	s_waitcnt lgkmcnt(0)
	s_barrier
	s_cmp_eq_u32 s36, 5
	s_cbranch_scc0 .Latt_nobar
	ds_read_b128 v[204:207], v170
	ds_read_b128 v[208:211], v170 offset:16
	ds_read_b128 v[212:215], v170 offset:32
	ds_read_b128 v[216:219], v170 offset:48
	ds_read_b128 v[220:223], v170 offset:64
	ds_read_b128 v[224:227], v170 offset:80
	ds_read_b128 v[228:231], v170 offset:96
	ds_read_b128 v[232:235], v170 offset:112
	ds_read_b32 v241, v171
	s_lshl_b32 s2, s37, 11
	s_lshl_b32 s3, s38, 7
	s_add_u32 s2, s2, s3
	s_add_u32 s90, s6, s2
	s_addc_u32 s91, s7, 0
	s_waitcnt lgkmcnt(0)
	v_div_scale_f32 v242, s[30:31], v241, v241, 1.0
	v_rcp_f32_e32 v243, v242
	v_div_scale_f32 v237, vcc, 1.0, v241, 1.0
	v_fma_f32 v238, -v242, v243, 1.0
	v_fmac_f32_e32 v243, v238, v243
	v_mul_f32_e32 v238, v237, v243
	v_fma_f32 v239, -v242, v238, v237
	v_fmac_f32_e32 v238, v239, v243
	v_fma_f32 v242, -v242, v238, v237
	v_div_fmas_f32 v242, v242, v243, v238
	v_div_fixup_f32 v241, v242, v241, 1.0
	v_mul_f32_e32 v204, v241, v204
	v_mul_f32_e32 v205, v241, v205
	v_mul_f32_e32 v206, v241, v206
	v_mul_f32_e32 v207, v241, v207
	v_mul_f32_e32 v208, v241, v208
	v_mul_f32_e32 v209, v241, v209
	v_mul_f32_e32 v210, v241, v210
	v_mul_f32_e32 v211, v241, v211
	v_mul_f32_e32 v212, v241, v212
	v_mul_f32_e32 v213, v241, v213
	v_mul_f32_e32 v214, v241, v214
	v_mul_f32_e32 v215, v241, v215
	v_mul_f32_e32 v216, v241, v216
	v_mul_f32_e32 v217, v241, v217
	v_mul_f32_e32 v218, v241, v218
	v_mul_f32_e32 v219, v241, v219
	v_mul_f32_e32 v220, v241, v220
	v_mul_f32_e32 v221, v241, v221
	v_mul_f32_e32 v222, v241, v222
	v_mul_f32_e32 v223, v241, v223
	v_mul_f32_e32 v224, v241, v224
	v_mul_f32_e32 v225, v241, v225
	v_mul_f32_e32 v226, v241, v226
	v_mul_f32_e32 v227, v241, v227
	v_mul_f32_e32 v228, v241, v228
	v_mul_f32_e32 v229, v241, v229
	v_mul_f32_e32 v230, v241, v230
	v_mul_f32_e32 v231, v241, v231
	v_mul_f32_e32 v232, v241, v232
	v_mul_f32_e32 v233, v241, v233
	v_mul_f32_e32 v234, v241, v234
	v_mul_f32_e32 v235, v241, v235
	v_cvt_pk_bf16_f32 v184, v204, v205
	v_cvt_pk_bf16_f32 v185, v206, v207
	v_cvt_pk_bf16_f32 v186, v208, v209
	v_cvt_pk_bf16_f32 v187, v210, v211
	v_cvt_pk_bf16_f32 v188, v212, v213
	v_cvt_pk_bf16_f32 v189, v214, v215
	v_cvt_pk_bf16_f32 v190, v216, v217
	v_cvt_pk_bf16_f32 v191, v218, v219
	v_cvt_pk_bf16_f32 v192, v220, v221
	v_cvt_pk_bf16_f32 v193, v222, v223
	v_cvt_pk_bf16_f32 v194, v224, v225
	v_cvt_pk_bf16_f32 v195, v226, v227
	v_cvt_pk_bf16_f32 v196, v228, v229
	v_cvt_pk_bf16_f32 v197, v230, v231
	v_cvt_pk_bf16_f32 v198, v232, v233
	v_cvt_pk_bf16_f32 v199, v234, v235
	global_store_dwordx4 v172, v[184:187], s[90:91] nt
	global_store_dwordx4 v172, v[188:191], s[90:91] offset:16 nt
	global_store_dwordx4 v172, v[192:195], s[90:91] offset:32 nt
	global_store_dwordx4 v172, v[196:199], s[90:91] offset:48 nt
	s_barrier
.Latt_nobar:
	s_cmp_eq_u32 s39, 0
	s_cbranch_scc1 .Latt_loop
	s_waitcnt vmcnt(0)
	s_branch .LBB0_365
